# in-projection epilogue: rotary table loads of row groups 1..6 issued with group 0 (one round trip), store-only waits counted
# speedup vs baseline: 1.0090x; 1.0090x over previous
;     DI void operator()(const pg8::f32x4 (&acc)[2][2][4][2], const pg8::Unit& u, int wr, int wc, int fr, int fq) const {
;     ...
;                 const int row = row0 + ai * 128 + m * 16;
;                 f32x2 cs[4];
;                 bool rot = false;
;                 if ((att || ret) && row < M_LAT) {
;                     rot = true;
;                     const int s = row & 4095;
;                     const f32x2* tp;
;                     if (att) { const int pos = (wc & 1) ? (s & 63) : (s >> 6); tp = tatt + pos * 16 + 4 * fq; }
;                     else { tp = tret + (size_t)s * 32 + 16 * (wc & 1) + 4 * fq; }
;                     const f32x4 t0 = *(const f32x4*)tp, t1 = *(const f32x4*)(tp + 2);
;                     cs[0] = (f32x2){t0.x, t0.y}; cs[1] = (f32x2){t0.z, t0.w}; cs[2] = (f32x2){t1.x, t1.y}; cs[3] = (f32x2){t1.z, t1.w};
.LBB0_129:
	s_lshl_b32 s19, s0, 8
	s_add_i32 s19, s19, s43
	v_or_b32_e32 v180, s19, v153
	s_and_b32 s21, s50, -2
	s_mov_b64 s[2:3], -1
	s_cmp_lg_u32 s21, 4
	v_cmp_gt_i32_e64 s[0:1], s59, v180
	s_cbranch_scc0 .LBB0_180
	s_cmp_lt_i32 s50, 4
	s_cselect_b64 vcc, -1, 0
	s_cmp_eq_u32 s21, 10
	s_cselect_b64 s[2:3], -1, 0
	s_or_b64 s[2:3], vcc, s[2:3]
	v_mov_b32_e32 v132, 0
	s_and_b64 s[28:29], s[2:3], s[0:1]
	v_lshlrev_b32_e32 v166, 3, v156
	v_mov_b32_e32 v133, v132
	v_mov_b32_e32 v134, v132
	v_mov_b32_e32 v135, v132
	v_mov_b32_e32 v128, v132
	v_mov_b32_e32 v129, v132
	v_mov_b32_e32 v130, v132
	v_mov_b32_e32 v131, v132
	s_and_saveexec_b64 s[0:1], s[28:29]
	s_cbranch_execz .LBB0_132
	v_bfe_u32 v129, v180, 6, 6
	v_and_b32_e32 v128, 0xfcf, v180
	v_cndmask_b32_e64 v129, v153, v129, s[6:7]
	v_lshlrev_b32_e32 v128, 5, v128
	v_lshlrev_b32_e32 v129, 4, v129
	v_cndmask_b32_e32 v128, v128, v129, vcc
	s_and_b64 s[26:27], vcc, exec
	s_cselect_b32 s27, s41, s49
	s_cselect_b32 s26, s40, s48
	v_lshlrev_b32_e32 v146, 3, v128
	v_lshl_add_u64 v[128:129], s[26:27], 0, v[146:147]
	v_mov_b32_e32 v167, v147
	v_lshl_add_u64 v[128:129], v[128:129], 0, v[166:167]
	global_load_dwordx4 v[132:135], v[128:129], off
	s_nop 0
	global_load_dwordx4 v[128:131], v[128:129], off offset:16
	v_or_b32_e32 v206, 0x10, v180
	v_bfe_u32 v207, v206, 6, 6
	v_and_b32_e32 v206, 0xfdf, v206
	v_cndmask_b32_e64 v207, v155, v207, s[6:7]
	v_lshlrev_b32_e32 v207, 4, v207
	v_lshlrev_b32_e32 v206, 5, v206
	v_cndmask_b32_e32 v206, v206, v207, vcc
	v_lshlrev_b32_e32 v206, 3, v206
	v_mov_b32_e32 v207, v147
	v_lshl_add_u64 v[206:207], s[26:27], 0, v[206:207]
	v_lshl_add_u64 v[206:207], v[206:207], 0, v[166:167]
	global_load_dwordx4 v[190:193], v[206:207], off
	global_load_dwordx4 v[194:197], v[206:207], off offset:16
	v_or_b32_e32 v206, 0x20, v180
	v_bfe_u32 v207, v206, 6, 6
	v_and_b32_e32 v206, 0xfef, v206
	v_cndmask_b32_e64 v207, v157, v207, s[6:7]
	v_lshlrev_b32_e32 v207, 4, v207
	v_lshlrev_b32_e32 v206, 5, v206
	v_cndmask_b32_e32 v206, v206, v207, vcc
	v_lshlrev_b32_e32 v206, 3, v206
	v_mov_b32_e32 v207, v147
	v_lshl_add_u64 v[206:207], s[26:27], 0, v[206:207]
	v_lshl_add_u64 v[206:207], v[206:207], 0, v[166:167]
	global_load_dwordx4 v[198:201], v[206:207], off
	global_load_dwordx4 v[202:205], v[206:207], off offset:16
	v_or_b32_e32 v206, 0x30, v180
	v_bfe_u32 v207, v206, 6, 6
	v_and_b32_e32 v206, 0xfff, v206
	v_cndmask_b32_e64 v207, v159, v207, s[6:7]
	v_lshlrev_b32_e32 v207, 4, v207
	v_lshlrev_b32_e32 v206, 5, v206
	v_cndmask_b32_e32 v206, v206, v207, vcc
	v_lshlrev_b32_e32 v206, 3, v206
	v_mov_b32_e32 v207, v147
	v_lshl_add_u64 v[206:207], s[26:27], 0, v[206:207]
	v_lshl_add_u64 v[206:207], v[206:207], 0, v[166:167]
	global_load_dwordx4 v[218:221], v[206:207], off
	global_load_dwordx4 v[222:225], v[206:207], off offset:16
	v_add_u32_e32 v206, 0x80, v180
	v_bfe_u32 v207, v206, 6, 6
	v_and_b32_e32 v206, 0xfcf, v206
	v_cndmask_b32_e64 v207, v153, v207, s[6:7]
	v_lshlrev_b32_e32 v207, 4, v207
	v_lshlrev_b32_e32 v206, 5, v206
	v_cndmask_b32_e32 v206, v206, v207, vcc
	v_lshlrev_b32_e32 v206, 3, v206
	v_mov_b32_e32 v207, v147
	v_lshl_add_u64 v[206:207], s[26:27], 0, v[206:207]
	v_lshl_add_u64 v[206:207], v[206:207], 0, v[166:167]
	global_load_dwordx4 v[226:229], v[206:207], off
	global_load_dwordx4 v[230:233], v[206:207], off offset:16
	v_add_u32_e32 v206, 0x90, v180
	v_bfe_u32 v207, v206, 6, 6
	v_and_b32_e32 v206, 0xfdf, v206
	v_cndmask_b32_e64 v207, v155, v207, s[6:7]
	v_lshlrev_b32_e32 v207, 4, v207
	v_lshlrev_b32_e32 v206, 5, v206
	v_cndmask_b32_e32 v206, v206, v207, vcc
	v_lshlrev_b32_e32 v206, 3, v206
	v_mov_b32_e32 v207, v147
	v_lshl_add_u64 v[206:207], s[26:27], 0, v[206:207]
	v_lshl_add_u64 v[206:207], v[206:207], 0, v[166:167]
	global_load_dwordx4 v[234:237], v[206:207], off
	global_load_dwordx4 v[238:241], v[206:207], off offset:16
	v_add_u32_e32 v206, 0xa0, v180
	v_bfe_u32 v207, v206, 6, 6
	v_and_b32_e32 v206, 0xfef, v206
	v_cndmask_b32_e64 v207, v157, v207, s[6:7]
	v_lshlrev_b32_e32 v207, 4, v207
	v_lshlrev_b32_e32 v206, 5, v206
	v_cndmask_b32_e32 v206, v206, v207, vcc
	v_lshlrev_b32_e32 v206, 3, v206
	v_mov_b32_e32 v207, v147
	v_lshl_add_u64 v[206:207], s[26:27], 0, v[206:207]
	v_lshl_add_u64 v[206:207], v[206:207], 0, v[166:167]
	global_load_dwordx4 v[242:245], v[206:207], off
	global_load_dwordx4 v[246:249], v[206:207], off offset:16

; DI unsigned pk2(float lo, float hi) { f32x2 v = {lo, hi}; bf16x2_t b = __builtin_convertvector(v, bf16x2_t); return __builtin_bit_cast(unsigned, b); }
;     DI void operator()(const pg8::f32x4 (&acc)[2][2][4][2], const pg8::Unit& u, int wr, int wc, int fr, int fq) const {
;     ...
;                 const int row = row0 + ai * 128 + m * 16;
;                 f32x2 cs[4];
;                 bool rot = false;
;                 if ((att || ret) && row < M_LAT) {
;                     rot = true;
;                     const int s = row & 4095;
;                     const f32x2* tp;
;                     if (att) { const int pos = (wc & 1) ? (s & 63) : (s >> 6); tp = tatt + pos * 16 + 4 * fq; }
;                     else { tp = tret + (size_t)s * 32 + 16 * (wc & 1) + 4 * fq; }
;                     const f32x4 t0 = *(const f32x4*)tp, t1 = *(const f32x4*)(tp + 2);
;                     cs[0] = (f32x2){t0.x, t0.y}; cs[1] = (f32x2){t0.z, t0.w}; cs[2] = (f32x2){t1.x, t1.y}; cs[3] = (f32x2){t1.z, t1.w};
;                 }
; #pragma unroll
;                 for (int bj = 0; bj < 2; ++bj) {
;                     float v[8];
; #pragma unroll
;                     for (int n = 0; n < 2; ++n)
; #pragma unroll
;                         for (int j = 0; j < 4; ++j) v[n * 4 + j] = acc[ai][bj][m][n][j];
;                     if (rot) {
; #pragma unroll
;                         for (int q = 0; q < 4; ++q) { const float h1 = v[2 * q], h2 = v[2 * q + 1]; v[2 * q] = h1 * cs[q].x - h2 * cs[q].y; v[2 * q + 1] = h2 * cs[q].x + h1 * cs[q].y; }
;                     }
;                     u32x4 w; w.x = pk2(v[0] * sc, v[1] * sc); w.y = pk2(v[2] * sc, v[3] * sc); w.z = pk2(v[4] * sc, v[5] * sc); w.w = pk2(v[6] * sc, v[7] * sc);
;                     *(u32x4*)(P + (size_t)row * NIN + pn * 256 + bj * 128 + wc * 32 + 8 * fq) = w;
;                 }
.LBB0_134:
	s_or_b64 exec, exec, s[0:1]
	s_cmp_eq_u32 s50, 11
	s_cselect_b64 s[0:1], -1, 0
	v_mov_b32_e32 v145, 0x3e000000
	s_cmp_gt_i32 s50, 1
	v_cndmask_b32_e64 v145, 1.0, v145, s[0:1]
	s_cselect_b64 s[0:1], -1, 0
	v_mov_b32_e32 v146, 0x3e38aa3b
	v_cndmask_b32_e64 v164, v146, v145, s[0:1]
	v_pk_mul_f32 v[150:151], v[164:165], v[168:169] op_sel_hi:[0,1]
	v_cvt_pk_bf16_f32 v182, v150, v151
	v_pk_mul_f32 v[150:151], v[164:165], v[170:171] op_sel_hi:[0,1]
	v_cvt_pk_bf16_f32 v183, v150, v151
	v_pk_mul_f32 v[150:151], v[164:165], v[172:173] op_sel_hi:[0,1]
	v_cvt_pk_bf16_f32 v184, v150, v151
	v_pk_mul_f32 v[150:151], v[164:165], v[174:175] op_sel_hi:[0,1]
	v_cvt_pk_bf16_f32 v185, v150, v151
	v_mov_b64_e32 v[150:151], s[74:75]
	v_readlane_b32 s76, v253, 6
	v_mad_i64_i32 v[150:151], s[0:1], v180, s72, v[150:151]
	v_readlane_b32 s77, v253, 7
	s_mov_b32 s1, s77
	s_lshl_b32 s0, s44, 1
	s_mov_b64 s[52:53], s[0:1]
	v_readlane_b32 s78, v253, 8
	v_readlane_b32 s79, v253, 9
	v_readlane_b32 s80, v253, 10
	v_readlane_b32 s81, v253, 11
	v_readlane_b32 s82, v253, 12
	v_readlane_b32 s83, v253, 13
	v_readlane_b32 s84, v253, 14
	v_readlane_b32 s85, v253, 15
	v_readlane_b32 s86, v253, 16
	v_readlane_b32 s87, v253, 17
	v_readlane_b32 s88, v253, 18
	v_readlane_b32 s89, v253, 19
	v_readlane_b32 s90, v253, 20
	v_readlane_b32 s91, v253, 21
	v_writelane_b32 v253, s52, 6
	s_lshl_b32 s26, s50, 8
	s_ashr_i32 s27, s26, 31
	v_writelane_b32 v253, s53, 7
	v_writelane_b32 v253, s54, 8
	v_writelane_b32 v253, s55, 9
	v_writelane_b32 v253, s56, 10
	v_writelane_b32 v253, s57, 11
	v_writelane_b32 v253, s58, 12
	v_writelane_b32 v253, s59, 13
	v_writelane_b32 v253, s60, 14
	v_writelane_b32 v253, s61, 15
	v_writelane_b32 v253, s62, 16
	v_writelane_b32 v253, s63, 17
	v_writelane_b32 v253, s64, 18
	v_lshl_add_u64 v[150:151], s[26:27], 1, v[150:151]
	v_writelane_b32 v253, s65, 19
	v_writelane_b32 v253, s66, 20
	v_lshl_add_u64 v[150:151], v[150:151], 0, s[0:1]
	v_lshlrev_b32_e32 v146, 1, v154
	v_writelane_b32 v253, s67, 21
	v_lshl_add_u64 v[168:169], v[150:151], 0, v[146:147]
	v_mov_b32_e32 v170, v116
	v_mov_b32_e32 v171, v117
	v_mov_b32_e32 v172, v118
	v_mov_b32_e32 v173, v119
	v_mov_b32_e32 v174, v112
	v_mov_b32_e32 v175, v113
	v_mov_b32_e32 v176, v114
	v_mov_b32_e32 v177, v115
	global_store_dwordx4 v[168:169], v[182:185], off
	s_and_saveexec_b64 s[0:1], s[28:29]
	s_cbranch_execz .LBB0_136
	s_waitcnt vmcnt(1)
	v_pk_mul_f32 v[182:183], v[116:117], v[132:133] op_sel:[1,1] op_sel_hi:[0,1]
	v_pk_fma_f32 v[170:171], v[116:117], v[132:133], v[182:183] op_sel_hi:[1,0,1]
	v_pk_mul_f32 v[150:151], v[116:117], v[132:133]
	v_mov_b32_e32 v170, v135
	v_pk_mul_f32 v[174:175], v[118:119], v[170:171] op_sel:[1,0] op_sel_hi:[0,0]
	v_mov_b32_e32 v170, v129
	v_pk_mul_f32 v[176:177], v[112:113], v[170:171] op_sel:[1,0] op_sel_hi:[0,0]
	v_mul_f32_e32 v170, v115, v131
	v_pk_fma_f32 v[172:173], v[118:119], v[134:135], v[174:175] op_sel_hi:[1,0,1] neg_lo:[0,0,1] neg_hi:[0,0,1]
	v_pk_fma_f32 v[184:185], v[118:119], v[134:135], v[174:175] op_sel_hi:[1,0,1]
	v_pk_fma_f32 v[174:175], v[112:113], v[128:129], v[176:177] op_sel_hi:[1,0,1] neg_lo:[0,0,1] neg_hi:[0,0,1]
	v_pk_fma_f32 v[186:187], v[112:113], v[128:129], v[176:177] op_sel_hi:[1,0,1]
	v_pk_fma_f32 v[176:177], v[114:115], v[130:131], v[170:171] op_sel_hi:[1,1,0] neg_lo:[0,0,1] neg_hi:[0,0,1]
	v_mul_f32_e32 v170, v114, v131
	v_pk_fma_f32 v[188:189], v[114:115], v[130:131], v[170:171] op_sel:[1,0,0] op_sel_hi:[0,1,0]
	v_sub_f32_e32 v170, v150, v182
	v_mov_b32_e32 v173, v185
	v_mov_b32_e32 v175, v187
	v_mov_b32_e32 v177, v188
.LBB0_136:
	s_or_b64 exec, exec, s[0:1]
	v_mov_b32_e32 v165, v164
	v_pk_mul_f32 v[150:151], v[164:165], v[170:171]
	s_nop 0
	v_cvt_pk_bf16_f32 v170, v150, v151
	v_pk_mul_f32 v[150:151], v[164:165], v[172:173]
	s_nop 0
	v_cvt_pk_bf16_f32 v171, v150, v151
	v_pk_mul_f32 v[150:151], v[164:165], v[174:175]
	s_nop 0
	v_cvt_pk_bf16_f32 v172, v150, v151
	v_pk_mul_f32 v[150:151], v[164:165], v[176:177]
	s_nop 0
	v_cvt_pk_bf16_f32 v173, v150, v151
	global_store_dwordx4 v[168:169], v[170:173], off offset:256
	v_or_b32_e32 v176, 16, v180
	v_cmp_gt_i32_e64 s[0:1], s59, v176
	s_and_b64 s[0:1], s[2:3], s[0:1]
	s_and_saveexec_b64 s[28:29], s[0:1]
	s_cbranch_execz .LBB0_138
	s_waitcnt vmcnt(2)
	v_bfe_u32 v129, v176, 6, 6
	v_and_b32_e32 v128, 0xfdf, v176
	v_cndmask_b32_e64 v129, v155, v129, s[6:7]
	v_lshlrev_b32_e32 v129, 4, v129
	v_lshlrev_b32_e32 v128, 5, v128
	v_cndmask_b32_e32 v128, v128, v129, vcc
	s_and_b64 s[52:53], vcc, exec
	s_cselect_b32 s53, s41, s49
	s_cselect_b32 s52, s40, s48
	v_lshlrev_b32_e32 v128, 3, v128
	v_mov_b32_e32 v129, v147
	v_lshl_add_u64 v[128:129], s[52:53], 0, v[128:129]
	v_mov_b32_e32 v167, v147
	v_lshl_add_u64 v[132:133], v[128:129], 0, v[166:167]
	v_mov_b32_e32 v128, v194
	v_mov_b32_e32 v129, v195
	v_mov_b32_e32 v130, v196
	v_mov_b32_e32 v131, v197
	s_nop 0
	v_mov_b32_e32 v132, v190
	v_mov_b32_e32 v133, v191
	v_mov_b32_e32 v134, v192
	v_mov_b32_e32 v135, v193
; DI unsigned pk2(float lo, float hi) { f32x2 v = {lo, hi}; bf16x2_t b = __builtin_convertvector(v, bf16x2_t); return __builtin_bit_cast(unsigned, b); }
;     DI void operator()(const pg8::f32x4 (&acc)[2][2][4][2], const pg8::Unit& u, int wr, int wc, int fr, int fq) const {
;     ...
;                 const int row = row0 + ai * 128 + m * 16;
;                 f32x2 cs[4];
;                 bool rot = false;
;                 if ((att || ret) && row < M_LAT) {
;                     rot = true;
;                     const int s = row & 4095;
;                     const f32x2* tp;
;                     if (att) { const int pos = (wc & 1) ? (s & 63) : (s >> 6); tp = tatt + pos * 16 + 4 * fq; }
;                     else { tp = tret + (size_t)s * 32 + 16 * (wc & 1) + 4 * fq; }
;                     const f32x4 t0 = *(const f32x4*)tp, t1 = *(const f32x4*)(tp + 2);
;                     cs[0] = (f32x2){t0.x, t0.y}; cs[1] = (f32x2){t0.z, t0.w}; cs[2] = (f32x2){t1.x, t1.y}; cs[3] = (f32x2){t1.z, t1.w};
;                 }
; #pragma unroll
;                 for (int bj = 0; bj < 2; ++bj) {
;                     float v[8];
; #pragma unroll
;                     for (int n = 0; n < 2; ++n)
; #pragma unroll
;                         for (int j = 0; j < 4; ++j) v[n * 4 + j] = acc[ai][bj][m][n][j];
;                     if (rot) {
; #pragma unroll
;                         for (int q = 0; q < 4; ++q) { const float h1 = v[2 * q], h2 = v[2 * q + 1]; v[2 * q] = h1 * cs[q].x - h2 * cs[q].y; v[2 * q + 1] = h2 * cs[q].x + h1 * cs[q].y; }
;                     }
;                     u32x4 w; w.x = pk2(v[0] * sc, v[1] * sc); w.y = pk2(v[2] * sc, v[3] * sc); w.z = pk2(v[4] * sc, v[5] * sc); w.w = pk2(v[6] * sc, v[7] * sc);
;                     *(u32x4*)(P + (size_t)row * NIN + pn * 256 + bj * 128 + wc * 32 + 8 * fq) = w;
;                 }
.LBB0_138:
	s_or_b64 exec, exec, s[28:29]
	v_mov_b32_e32 v168, v108
	v_mov_b32_e32 v169, v109
	v_mov_b32_e32 v170, v110
	v_mov_b32_e32 v171, v111
	v_mov_b32_e32 v172, v104
	v_mov_b32_e32 v173, v105
	v_mov_b32_e32 v174, v106
	v_mov_b32_e32 v175, v107
	s_and_saveexec_b64 s[28:29], s[0:1]
	s_cbranch_execz .LBB0_140
	s_waitcnt vmcnt(2)
	v_pk_mul_f32 v[182:183], v[108:109], v[132:133] op_sel:[1,1] op_sel_hi:[0,1]
	v_pk_fma_f32 v[168:169], v[108:109], v[132:133], v[182:183] op_sel_hi:[1,0,1]
	v_pk_mul_f32 v[150:151], v[108:109], v[132:133]
	v_mov_b32_e32 v168, v135
	v_pk_mul_f32 v[172:173], v[110:111], v[168:169] op_sel:[1,0] op_sel_hi:[0,0]
	v_mov_b32_e32 v168, v129
	v_pk_mul_f32 v[174:175], v[104:105], v[168:169] op_sel:[1,0] op_sel_hi:[0,0]
	v_mul_f32_e32 v168, v107, v131
	v_pk_fma_f32 v[170:171], v[110:111], v[134:135], v[172:173] op_sel_hi:[1,0,1] neg_lo:[0,0,1] neg_hi:[0,0,1]
	v_pk_fma_f32 v[184:185], v[110:111], v[134:135], v[172:173] op_sel_hi:[1,0,1]
	v_pk_fma_f32 v[172:173], v[104:105], v[128:129], v[174:175] op_sel_hi:[1,0,1] neg_lo:[0,0,1] neg_hi:[0,0,1]
	v_pk_fma_f32 v[186:187], v[104:105], v[128:129], v[174:175] op_sel_hi:[1,0,1]
	v_pk_fma_f32 v[174:175], v[106:107], v[130:131], v[168:169] op_sel_hi:[1,1,0] neg_lo:[0,0,1] neg_hi:[0,0,1]
	v_mul_f32_e32 v168, v106, v131
	v_pk_fma_f32 v[188:189], v[106:107], v[130:131], v[168:169] op_sel:[1,0,0] op_sel_hi:[0,1,0]
	v_sub_f32_e32 v168, v150, v182
	v_mov_b32_e32 v171, v185
	v_mov_b32_e32 v173, v187
	v_mov_b32_e32 v175, v188
.LBB0_140:
	s_or_b64 exec, exec, s[28:29]
	v_pk_mul_f32 v[150:151], v[164:165], v[168:169]
	v_readlane_b32 s76, v253, 6
	v_cvt_pk_bf16_f32 v182, v150, v151
	v_pk_mul_f32 v[150:151], v[164:165], v[170:171]
	v_readlane_b32 s77, v253, 7
	v_cvt_pk_bf16_f32 v183, v150, v151
	v_pk_mul_f32 v[150:151], v[164:165], v[172:173]
	v_mov_b32_e32 v170, v100
	v_cvt_pk_bf16_f32 v184, v150, v151
	v_pk_mul_f32 v[150:151], v[164:165], v[174:175]
	v_mov_b32_e32 v171, v101
	v_cvt_pk_bf16_f32 v185, v150, v151
	v_mov_b64_e32 v[150:151], s[74:75]
	v_mad_i64_i32 v[150:151], s[28:29], v176, s72, v[150:151]
	v_lshl_add_u64 v[150:151], s[26:27], 1, v[150:151]
	v_lshl_add_u64 v[150:151], v[150:151], 0, s[76:77]
	v_lshl_add_u64 v[168:169], v[150:151], 0, v[146:147]
	v_mov_b32_e32 v172, v102
	v_mov_b32_e32 v173, v103
	v_mov_b32_e32 v174, v96
	v_mov_b32_e32 v175, v97
	v_mov_b32_e32 v176, v98
	v_mov_b32_e32 v177, v99
	v_readlane_b32 s78, v253, 8
	v_readlane_b32 s79, v253, 9
	v_readlane_b32 s80, v253, 10
	v_readlane_b32 s81, v253, 11
	v_readlane_b32 s82, v253, 12
	v_readlane_b32 s83, v253, 13
	v_readlane_b32 s84, v253, 14
	v_readlane_b32 s85, v253, 15
	v_readlane_b32 s86, v253, 16
	v_readlane_b32 s87, v253, 17
	v_readlane_b32 s88, v253, 18
	v_readlane_b32 s89, v253, 19
	v_readlane_b32 s90, v253, 20
	v_readlane_b32 s91, v253, 21
	global_store_dwordx4 v[168:169], v[182:185], off
	s_and_saveexec_b64 s[28:29], s[0:1]
	s_cbranch_execz .LBB0_142
	s_waitcnt vmcnt(1)
	v_pk_mul_f32 v[182:183], v[100:101], v[132:133] op_sel:[1,1] op_sel_hi:[0,1]
	v_pk_fma_f32 v[170:171], v[100:101], v[132:133], v[182:183] op_sel_hi:[1,0,1]
	v_pk_mul_f32 v[150:151], v[100:101], v[132:133]
	v_mov_b32_e32 v170, v135
	v_pk_mul_f32 v[174:175], v[102:103], v[170:171] op_sel:[1,0] op_sel_hi:[0,0]
	v_mov_b32_e32 v170, v129
	v_pk_mul_f32 v[176:177], v[96:97], v[170:171] op_sel:[1,0] op_sel_hi:[0,0]
	v_mul_f32_e32 v170, v99, v131
	v_pk_fma_f32 v[172:173], v[102:103], v[134:135], v[174:175] op_sel_hi:[1,0,1] neg_lo:[0,0,1] neg_hi:[0,0,1]
	v_pk_fma_f32 v[184:185], v[102:103], v[134:135], v[174:175] op_sel_hi:[1,0,1]
	v_pk_fma_f32 v[174:175], v[96:97], v[128:129], v[176:177] op_sel_hi:[1,0,1] neg_lo:[0,0,1] neg_hi:[0,0,1]
	v_pk_fma_f32 v[186:187], v[96:97], v[128:129], v[176:177] op_sel_hi:[1,0,1]
	v_pk_fma_f32 v[176:177], v[98:99], v[130:131], v[170:171] op_sel_hi:[1,1,0] neg_lo:[0,0,1] neg_hi:[0,0,1]
	v_mul_f32_e32 v170, v98, v131
	v_pk_fma_f32 v[188:189], v[98:99], v[130:131], v[170:171] op_sel:[1,0,0] op_sel_hi:[0,1,0]
	v_sub_f32_e32 v170, v150, v182
	v_mov_b32_e32 v173, v185
	v_mov_b32_e32 v175, v187
	v_mov_b32_e32 v177, v188
.LBB0_142:
	s_or_b64 exec, exec, s[28:29]
	v_pk_mul_f32 v[150:151], v[164:165], v[170:171]
	s_nop 0
	v_cvt_pk_bf16_f32 v170, v150, v151
	v_pk_mul_f32 v[150:151], v[164:165], v[172:173]
	s_nop 0
	v_cvt_pk_bf16_f32 v171, v150, v151
	v_pk_mul_f32 v[150:151], v[164:165], v[174:175]
	s_nop 0
	v_cvt_pk_bf16_f32 v172, v150, v151
	v_pk_mul_f32 v[150:151], v[164:165], v[176:177]
	s_nop 0
	v_cvt_pk_bf16_f32 v173, v150, v151
	global_store_dwordx4 v[168:169], v[170:173], off offset:256
	v_or_b32_e32 v176, 32, v180
	v_cmp_gt_i32_e64 s[0:1], s59, v176
	s_and_b64 s[0:1], s[2:3], s[0:1]
	s_and_saveexec_b64 s[28:29], s[0:1]
	s_cbranch_execz .LBB0_144
	s_waitcnt vmcnt(2)
	v_bfe_u32 v129, v176, 6, 6
	v_and_b32_e32 v128, 0xfef, v176
	v_cndmask_b32_e64 v129, v157, v129, s[6:7]
	v_lshlrev_b32_e32 v129, 4, v129
	v_lshlrev_b32_e32 v128, 5, v128
	v_cndmask_b32_e32 v128, v128, v129, vcc
	s_and_b64 s[52:53], vcc, exec
	s_cselect_b32 s53, s41, s49
	s_cselect_b32 s52, s40, s48
	v_lshlrev_b32_e32 v128, 3, v128
	v_mov_b32_e32 v129, v147
	v_lshl_add_u64 v[128:129], s[52:53], 0, v[128:129]
	v_mov_b32_e32 v167, v147
	v_lshl_add_u64 v[132:133], v[128:129], 0, v[166:167]
	v_mov_b32_e32 v128, v202
	v_mov_b32_e32 v129, v203
	v_mov_b32_e32 v130, v204
	v_mov_b32_e32 v131, v205
	s_nop 0
	v_mov_b32_e32 v132, v198
	v_mov_b32_e32 v133, v199
	v_mov_b32_e32 v134, v200
	v_mov_b32_e32 v135, v201
; DI unsigned pk2(float lo, float hi) { f32x2 v = {lo, hi}; bf16x2_t b = __builtin_convertvector(v, bf16x2_t); return __builtin_bit_cast(unsigned, b); }
;     DI void operator()(const pg8::f32x4 (&acc)[2][2][4][2], const pg8::Unit& u, int wr, int wc, int fr, int fq) const {
;     ...
;                 const int row = row0 + ai * 128 + m * 16;
;                 f32x2 cs[4];
;                 bool rot = false;
;                 if ((att || ret) && row < M_LAT) {
;                     rot = true;
;                     const int s = row & 4095;
;                     const f32x2* tp;
;                     if (att) { const int pos = (wc & 1) ? (s & 63) : (s >> 6); tp = tatt + pos * 16 + 4 * fq; }
;                     else { tp = tret + (size_t)s * 32 + 16 * (wc & 1) + 4 * fq; }
;                     const f32x4 t0 = *(const f32x4*)tp, t1 = *(const f32x4*)(tp + 2);
;                     cs[0] = (f32x2){t0.x, t0.y}; cs[1] = (f32x2){t0.z, t0.w}; cs[2] = (f32x2){t1.x, t1.y}; cs[3] = (f32x2){t1.z, t1.w};
;                 }
; #pragma unroll
;                 for (int bj = 0; bj < 2; ++bj) {
;                     float v[8];
; #pragma unroll
;                     for (int n = 0; n < 2; ++n)
; #pragma unroll
;                         for (int j = 0; j < 4; ++j) v[n * 4 + j] = acc[ai][bj][m][n][j];
;                     if (rot) {
; #pragma unroll
;                         for (int q = 0; q < 4; ++q) { const float h1 = v[2 * q], h2 = v[2 * q + 1]; v[2 * q] = h1 * cs[q].x - h2 * cs[q].y; v[2 * q + 1] = h2 * cs[q].x + h1 * cs[q].y; }
;                     }
;                     u32x4 w; w.x = pk2(v[0] * sc, v[1] * sc); w.y = pk2(v[2] * sc, v[3] * sc); w.z = pk2(v[4] * sc, v[5] * sc); w.w = pk2(v[6] * sc, v[7] * sc);
;                     *(u32x4*)(P + (size_t)row * NIN + pn * 256 + bj * 128 + wc * 32 + 8 * fq) = w;
;                 }
.LBB0_144:
	s_or_b64 exec, exec, s[28:29]
	v_mov_b32_e32 v168, v92
	v_mov_b32_e32 v169, v93
	v_mov_b32_e32 v170, v94
	v_mov_b32_e32 v171, v95
	v_mov_b32_e32 v172, v88
	v_mov_b32_e32 v173, v89
	v_mov_b32_e32 v174, v90
	v_mov_b32_e32 v175, v91
	s_and_saveexec_b64 s[28:29], s[0:1]
	s_cbranch_execz .LBB0_146
	s_waitcnt vmcnt(2)
	v_pk_mul_f32 v[182:183], v[92:93], v[132:133] op_sel:[1,1] op_sel_hi:[0,1]
	v_pk_fma_f32 v[168:169], v[92:93], v[132:133], v[182:183] op_sel_hi:[1,0,1]
	v_pk_mul_f32 v[150:151], v[92:93], v[132:133]
	v_mov_b32_e32 v168, v135
	v_pk_mul_f32 v[172:173], v[94:95], v[168:169] op_sel:[1,0] op_sel_hi:[0,0]
	v_mov_b32_e32 v168, v129
	v_pk_mul_f32 v[174:175], v[88:89], v[168:169] op_sel:[1,0] op_sel_hi:[0,0]
	v_mul_f32_e32 v168, v91, v131
	v_pk_fma_f32 v[170:171], v[94:95], v[134:135], v[172:173] op_sel_hi:[1,0,1] neg_lo:[0,0,1] neg_hi:[0,0,1]
	v_pk_fma_f32 v[184:185], v[94:95], v[134:135], v[172:173] op_sel_hi:[1,0,1]
	v_pk_fma_f32 v[172:173], v[88:89], v[128:129], v[174:175] op_sel_hi:[1,0,1] neg_lo:[0,0,1] neg_hi:[0,0,1]
	v_pk_fma_f32 v[186:187], v[88:89], v[128:129], v[174:175] op_sel_hi:[1,0,1]
	v_pk_fma_f32 v[174:175], v[90:91], v[130:131], v[168:169] op_sel_hi:[1,1,0] neg_lo:[0,0,1] neg_hi:[0,0,1]
	v_mul_f32_e32 v168, v90, v131
	v_pk_fma_f32 v[188:189], v[90:91], v[130:131], v[168:169] op_sel:[1,0,0] op_sel_hi:[0,1,0]
	v_sub_f32_e32 v168, v150, v182
	v_mov_b32_e32 v171, v185
	v_mov_b32_e32 v173, v187
	v_mov_b32_e32 v175, v188
.LBB0_146:
	s_or_b64 exec, exec, s[28:29]
	v_pk_mul_f32 v[150:151], v[164:165], v[168:169]
	v_readlane_b32 s76, v253, 6
	v_cvt_pk_bf16_f32 v182, v150, v151
	v_pk_mul_f32 v[150:151], v[164:165], v[170:171]
	v_readlane_b32 s77, v253, 7
	v_cvt_pk_bf16_f32 v183, v150, v151
	v_pk_mul_f32 v[150:151], v[164:165], v[172:173]
	v_mov_b32_e32 v170, v84
	v_cvt_pk_bf16_f32 v184, v150, v151
	v_pk_mul_f32 v[150:151], v[164:165], v[174:175]
	v_mov_b32_e32 v171, v85
	v_cvt_pk_bf16_f32 v185, v150, v151
	v_mov_b64_e32 v[150:151], s[74:75]
	v_mad_i64_i32 v[150:151], s[28:29], v176, s72, v[150:151]
	v_lshl_add_u64 v[150:151], s[26:27], 1, v[150:151]
	v_lshl_add_u64 v[150:151], v[150:151], 0, s[76:77]
	v_lshl_add_u64 v[168:169], v[150:151], 0, v[146:147]
	v_mov_b32_e32 v172, v86
	v_mov_b32_e32 v173, v87
	v_mov_b32_e32 v174, v80
	v_mov_b32_e32 v175, v81
	v_mov_b32_e32 v176, v82
	v_mov_b32_e32 v177, v83
	v_readlane_b32 s78, v253, 8
	v_readlane_b32 s79, v253, 9
	v_readlane_b32 s80, v253, 10
	v_readlane_b32 s81, v253, 11
	v_readlane_b32 s82, v253, 12
	v_readlane_b32 s83, v253, 13
	v_readlane_b32 s84, v253, 14
	v_readlane_b32 s85, v253, 15
	v_readlane_b32 s86, v253, 16
	v_readlane_b32 s87, v253, 17
	v_readlane_b32 s88, v253, 18
	v_readlane_b32 s89, v253, 19
	v_readlane_b32 s90, v253, 20
	v_readlane_b32 s91, v253, 21
	global_store_dwordx4 v[168:169], v[182:185], off
	s_and_saveexec_b64 s[28:29], s[0:1]
	s_cbranch_execz .LBB0_148
	s_waitcnt vmcnt(1)
	v_pk_mul_f32 v[182:183], v[84:85], v[132:133] op_sel:[1,1] op_sel_hi:[0,1]
	v_pk_fma_f32 v[170:171], v[84:85], v[132:133], v[182:183] op_sel_hi:[1,0,1]
	v_pk_mul_f32 v[150:151], v[84:85], v[132:133]
	v_mov_b32_e32 v170, v135
	v_pk_mul_f32 v[174:175], v[86:87], v[170:171] op_sel:[1,0] op_sel_hi:[0,0]
	v_mov_b32_e32 v170, v129
	v_pk_mul_f32 v[176:177], v[80:81], v[170:171] op_sel:[1,0] op_sel_hi:[0,0]
	v_mul_f32_e32 v170, v83, v131
	v_pk_fma_f32 v[172:173], v[86:87], v[134:135], v[174:175] op_sel_hi:[1,0,1] neg_lo:[0,0,1] neg_hi:[0,0,1]
	v_pk_fma_f32 v[184:185], v[86:87], v[134:135], v[174:175] op_sel_hi:[1,0,1]
	v_pk_fma_f32 v[174:175], v[80:81], v[128:129], v[176:177] op_sel_hi:[1,0,1] neg_lo:[0,0,1] neg_hi:[0,0,1]
	v_pk_fma_f32 v[186:187], v[80:81], v[128:129], v[176:177] op_sel_hi:[1,0,1]
	v_pk_fma_f32 v[176:177], v[82:83], v[130:131], v[170:171] op_sel_hi:[1,1,0] neg_lo:[0,0,1] neg_hi:[0,0,1]
	v_mul_f32_e32 v170, v82, v131
	v_pk_fma_f32 v[188:189], v[82:83], v[130:131], v[170:171] op_sel:[1,0,0] op_sel_hi:[0,1,0]
	v_sub_f32_e32 v170, v150, v182
	v_mov_b32_e32 v173, v185
	v_mov_b32_e32 v175, v187
	v_mov_b32_e32 v177, v188
.LBB0_148:
	s_or_b64 exec, exec, s[28:29]
	v_pk_mul_f32 v[150:151], v[164:165], v[170:171]
	s_nop 0
	v_cvt_pk_bf16_f32 v170, v150, v151
	v_pk_mul_f32 v[150:151], v[164:165], v[172:173]
	s_nop 0
	v_cvt_pk_bf16_f32 v171, v150, v151
	v_pk_mul_f32 v[150:151], v[164:165], v[174:175]
	s_nop 0
	v_cvt_pk_bf16_f32 v172, v150, v151
	v_pk_mul_f32 v[150:151], v[164:165], v[176:177]
	s_nop 0
	v_cvt_pk_bf16_f32 v173, v150, v151
	global_store_dwordx4 v[168:169], v[170:173], off offset:256
	v_or_b32_e32 v176, 48, v180
	v_cmp_gt_i32_e64 s[0:1], s59, v176
	s_and_b64 s[0:1], s[2:3], s[0:1]
	s_and_saveexec_b64 s[28:29], s[0:1]
	s_cbranch_execz .LBB0_150
	s_waitcnt vmcnt(2)
	v_bfe_u32 v129, v176, 6, 6
	v_and_b32_e32 v128, 0xfff, v176
	v_cndmask_b32_e64 v129, v159, v129, s[6:7]
	v_lshlrev_b32_e32 v129, 4, v129
	v_lshlrev_b32_e32 v128, 5, v128
	v_cndmask_b32_e32 v128, v128, v129, vcc
	s_and_b64 s[52:53], vcc, exec
	s_cselect_b32 s53, s41, s49
	s_cselect_b32 s52, s40, s48
	v_lshlrev_b32_e32 v128, 3, v128
	v_mov_b32_e32 v129, v147
	v_lshl_add_u64 v[128:129], s[52:53], 0, v[128:129]
	v_mov_b32_e32 v167, v147
	v_lshl_add_u64 v[132:133], v[128:129], 0, v[166:167]
	v_mov_b32_e32 v128, v222
	v_mov_b32_e32 v129, v223
	v_mov_b32_e32 v130, v224
	v_mov_b32_e32 v131, v225
	s_nop 0
	v_mov_b32_e32 v132, v218
	v_mov_b32_e32 v133, v219
	v_mov_b32_e32 v134, v220
	v_mov_b32_e32 v135, v221
; DI unsigned pk2(float lo, float hi) { f32x2 v = {lo, hi}; bf16x2_t b = __builtin_convertvector(v, bf16x2_t); return __builtin_bit_cast(unsigned, b); }
;     DI void operator()(const pg8::f32x4 (&acc)[2][2][4][2], const pg8::Unit& u, int wr, int wc, int fr, int fq) const {
;     ...
;                 const int row = row0 + ai * 128 + m * 16;
;                 f32x2 cs[4];
;                 bool rot = false;
;                 if ((att || ret) && row < M_LAT) {
;                     rot = true;
;                     const int s = row & 4095;
;                     const f32x2* tp;
;                     if (att) { const int pos = (wc & 1) ? (s & 63) : (s >> 6); tp = tatt + pos * 16 + 4 * fq; }
;                     else { tp = tret + (size_t)s * 32 + 16 * (wc & 1) + 4 * fq; }
;                     const f32x4 t0 = *(const f32x4*)tp, t1 = *(const f32x4*)(tp + 2);
;                     cs[0] = (f32x2){t0.x, t0.y}; cs[1] = (f32x2){t0.z, t0.w}; cs[2] = (f32x2){t1.x, t1.y}; cs[3] = (f32x2){t1.z, t1.w};
;                 }
; #pragma unroll
;                 for (int bj = 0; bj < 2; ++bj) {
;                     float v[8];
; #pragma unroll
;                     for (int n = 0; n < 2; ++n)
; #pragma unroll
;                         for (int j = 0; j < 4; ++j) v[n * 4 + j] = acc[ai][bj][m][n][j];
;                     if (rot) {
; #pragma unroll
;                         for (int q = 0; q < 4; ++q) { const float h1 = v[2 * q], h2 = v[2 * q + 1]; v[2 * q] = h1 * cs[q].x - h2 * cs[q].y; v[2 * q + 1] = h2 * cs[q].x + h1 * cs[q].y; }
;                     }
;                     u32x4 w; w.x = pk2(v[0] * sc, v[1] * sc); w.y = pk2(v[2] * sc, v[3] * sc); w.z = pk2(v[4] * sc, v[5] * sc); w.w = pk2(v[6] * sc, v[7] * sc);
;                     *(u32x4*)(P + (size_t)row * NIN + pn * 256 + bj * 128 + wc * 32 + 8 * fq) = w;
;                 }
.LBB0_150:
	s_or_b64 exec, exec, s[28:29]
	v_mov_b32_e32 v168, v76
	v_mov_b32_e32 v169, v77
	v_mov_b32_e32 v170, v78
	v_mov_b32_e32 v171, v79
	v_mov_b32_e32 v172, v72
	v_mov_b32_e32 v173, v73
	v_mov_b32_e32 v174, v74
	v_mov_b32_e32 v175, v75
	s_and_saveexec_b64 s[28:29], s[0:1]
	s_cbranch_execz .LBB0_152
	s_waitcnt vmcnt(2)
	v_pk_mul_f32 v[182:183], v[76:77], v[132:133] op_sel:[1,1] op_sel_hi:[0,1]
	v_pk_fma_f32 v[168:169], v[76:77], v[132:133], v[182:183] op_sel_hi:[1,0,1]
	v_pk_mul_f32 v[150:151], v[76:77], v[132:133]
	v_mov_b32_e32 v168, v135
	v_pk_mul_f32 v[172:173], v[78:79], v[168:169] op_sel:[1,0] op_sel_hi:[0,0]
	v_mov_b32_e32 v168, v129
	v_pk_mul_f32 v[174:175], v[72:73], v[168:169] op_sel:[1,0] op_sel_hi:[0,0]
	v_mul_f32_e32 v168, v75, v131
	v_pk_fma_f32 v[170:171], v[78:79], v[134:135], v[172:173] op_sel_hi:[1,0,1] neg_lo:[0,0,1] neg_hi:[0,0,1]
	v_pk_fma_f32 v[184:185], v[78:79], v[134:135], v[172:173] op_sel_hi:[1,0,1]
	v_pk_fma_f32 v[172:173], v[72:73], v[128:129], v[174:175] op_sel_hi:[1,0,1] neg_lo:[0,0,1] neg_hi:[0,0,1]
	v_pk_fma_f32 v[186:187], v[72:73], v[128:129], v[174:175] op_sel_hi:[1,0,1]
	v_pk_fma_f32 v[174:175], v[74:75], v[130:131], v[168:169] op_sel_hi:[1,1,0] neg_lo:[0,0,1] neg_hi:[0,0,1]
	v_mul_f32_e32 v168, v74, v131
	v_pk_fma_f32 v[188:189], v[74:75], v[130:131], v[168:169] op_sel:[1,0,0] op_sel_hi:[0,1,0]
	v_sub_f32_e32 v168, v150, v182
	v_mov_b32_e32 v171, v185
	v_mov_b32_e32 v173, v187
	v_mov_b32_e32 v175, v188
.LBB0_152:
	s_or_b64 exec, exec, s[28:29]
	v_pk_mul_f32 v[150:151], v[164:165], v[168:169]
	v_readlane_b32 s76, v253, 6
	v_cvt_pk_bf16_f32 v182, v150, v151
	v_pk_mul_f32 v[150:151], v[164:165], v[170:171]
	v_readlane_b32 s77, v253, 7
	v_cvt_pk_bf16_f32 v183, v150, v151
	v_pk_mul_f32 v[150:151], v[164:165], v[172:173]
	v_mov_b32_e32 v170, v68
	v_cvt_pk_bf16_f32 v184, v150, v151
	v_pk_mul_f32 v[150:151], v[164:165], v[174:175]
	v_mov_b32_e32 v171, v69
	v_cvt_pk_bf16_f32 v185, v150, v151
	v_mov_b64_e32 v[150:151], s[74:75]
	v_mad_i64_i32 v[150:151], s[28:29], v176, s72, v[150:151]
	v_lshl_add_u64 v[150:151], s[26:27], 1, v[150:151]
	v_lshl_add_u64 v[150:151], v[150:151], 0, s[76:77]
	v_lshl_add_u64 v[168:169], v[150:151], 0, v[146:147]
	v_mov_b32_e32 v172, v70
	v_mov_b32_e32 v173, v71
	v_mov_b32_e32 v174, v64
	v_mov_b32_e32 v175, v65
	v_mov_b32_e32 v176, v66
	v_mov_b32_e32 v177, v67
	v_readlane_b32 s78, v253, 8
	v_readlane_b32 s79, v253, 9
	v_readlane_b32 s80, v253, 10
	v_readlane_b32 s81, v253, 11
	v_readlane_b32 s82, v253, 12
	v_readlane_b32 s83, v253, 13
	v_readlane_b32 s84, v253, 14
	v_readlane_b32 s85, v253, 15
	v_readlane_b32 s86, v253, 16
	v_readlane_b32 s87, v253, 17
	v_readlane_b32 s88, v253, 18
	v_readlane_b32 s89, v253, 19
	v_readlane_b32 s90, v253, 20
	v_readlane_b32 s91, v253, 21
	global_store_dwordx4 v[168:169], v[182:185], off
	s_and_saveexec_b64 s[28:29], s[0:1]
	s_cbranch_execz .LBB0_154
	s_waitcnt vmcnt(1)
	v_pk_mul_f32 v[182:183], v[68:69], v[132:133] op_sel:[1,1] op_sel_hi:[0,1]
	v_pk_fma_f32 v[170:171], v[68:69], v[132:133], v[182:183] op_sel_hi:[1,0,1]
	v_pk_mul_f32 v[150:151], v[68:69], v[132:133]
	v_mov_b32_e32 v170, v135
	v_pk_mul_f32 v[174:175], v[70:71], v[170:171] op_sel:[1,0] op_sel_hi:[0,0]
	v_mov_b32_e32 v170, v129
	v_pk_mul_f32 v[176:177], v[64:65], v[170:171] op_sel:[1,0] op_sel_hi:[0,0]
	v_mul_f32_e32 v170, v67, v131
	v_pk_fma_f32 v[172:173], v[70:71], v[134:135], v[174:175] op_sel_hi:[1,0,1] neg_lo:[0,0,1] neg_hi:[0,0,1]
	v_pk_fma_f32 v[184:185], v[70:71], v[134:135], v[174:175] op_sel_hi:[1,0,1]
	v_pk_fma_f32 v[174:175], v[64:65], v[128:129], v[176:177] op_sel_hi:[1,0,1] neg_lo:[0,0,1] neg_hi:[0,0,1]
	v_pk_fma_f32 v[186:187], v[64:65], v[128:129], v[176:177] op_sel_hi:[1,0,1]
	v_pk_fma_f32 v[176:177], v[66:67], v[130:131], v[170:171] op_sel_hi:[1,1,0] neg_lo:[0,0,1] neg_hi:[0,0,1]
	v_mul_f32_e32 v170, v66, v131
	v_pk_fma_f32 v[188:189], v[66:67], v[130:131], v[170:171] op_sel:[1,0,0] op_sel_hi:[0,1,0]
	v_sub_f32_e32 v170, v150, v182
	v_mov_b32_e32 v173, v185
	v_mov_b32_e32 v175, v187
	v_mov_b32_e32 v177, v188
.LBB0_154:
	s_or_b64 exec, exec, s[28:29]
	v_pk_mul_f32 v[150:151], v[164:165], v[170:171]
	s_nop 0
	v_cvt_pk_bf16_f32 v170, v150, v151
	v_pk_mul_f32 v[150:151], v[164:165], v[172:173]
	s_nop 0
	v_cvt_pk_bf16_f32 v171, v150, v151
	v_pk_mul_f32 v[150:151], v[164:165], v[174:175]
	s_nop 0
	v_cvt_pk_bf16_f32 v172, v150, v151
	v_pk_mul_f32 v[150:151], v[164:165], v[176:177]
	s_nop 0
	v_cvt_pk_bf16_f32 v173, v150, v151
	global_store_dwordx4 v[168:169], v[170:173], off offset:256
	s_movk_i32 s0, 0x7f80
	v_cmp_gt_i32_e64 s[0:1], s0, v180
	v_add_u32_e32 v176, 0x80, v180
	s_and_b64 s[0:1], s[2:3], s[0:1]
	s_and_saveexec_b64 s[28:29], s[0:1]
	s_cbranch_execz .LBB0_156
	s_waitcnt vmcnt(2)
	v_bfe_u32 v129, v176, 6, 6
	v_and_b32_e32 v128, 0xfcf, v176
	v_cndmask_b32_e64 v129, v153, v129, s[6:7]
	v_lshlrev_b32_e32 v129, 4, v129
	v_lshlrev_b32_e32 v128, 5, v128
	v_cndmask_b32_e32 v128, v128, v129, vcc
	s_and_b64 s[52:53], vcc, exec
	s_cselect_b32 s53, s41, s49
	s_cselect_b32 s52, s40, s48
	v_lshlrev_b32_e32 v128, 3, v128
	v_mov_b32_e32 v129, v147
	v_lshl_add_u64 v[128:129], s[52:53], 0, v[128:129]
	v_mov_b32_e32 v167, v147
	v_lshl_add_u64 v[132:133], v[128:129], 0, v[166:167]
	v_mov_b32_e32 v128, v230
	v_mov_b32_e32 v129, v231
	v_mov_b32_e32 v130, v232
	v_mov_b32_e32 v131, v233
	s_nop 0
	v_mov_b32_e32 v132, v226
	v_mov_b32_e32 v133, v227
	v_mov_b32_e32 v134, v228
	v_mov_b32_e32 v135, v229
; DI unsigned pk2(float lo, float hi) { f32x2 v = {lo, hi}; bf16x2_t b = __builtin_convertvector(v, bf16x2_t); return __builtin_bit_cast(unsigned, b); }
;     DI void operator()(const pg8::f32x4 (&acc)[2][2][4][2], const pg8::Unit& u, int wr, int wc, int fr, int fq) const {
;     ...
;                 const int row = row0 + ai * 128 + m * 16;
;                 f32x2 cs[4];
;                 bool rot = false;
;                 if ((att || ret) && row < M_LAT) {
;                     rot = true;
;                     const int s = row & 4095;
;                     const f32x2* tp;
;                     if (att) { const int pos = (wc & 1) ? (s & 63) : (s >> 6); tp = tatt + pos * 16 + 4 * fq; }
;                     else { tp = tret + (size_t)s * 32 + 16 * (wc & 1) + 4 * fq; }
;                     const f32x4 t0 = *(const f32x4*)tp, t1 = *(const f32x4*)(tp + 2);
;                     cs[0] = (f32x2){t0.x, t0.y}; cs[1] = (f32x2){t0.z, t0.w}; cs[2] = (f32x2){t1.x, t1.y}; cs[3] = (f32x2){t1.z, t1.w};
;                 }
; #pragma unroll
;                 for (int bj = 0; bj < 2; ++bj) {
;                     float v[8];
; #pragma unroll
;                     for (int n = 0; n < 2; ++n)
; #pragma unroll
;                         for (int j = 0; j < 4; ++j) v[n * 4 + j] = acc[ai][bj][m][n][j];
;                     if (rot) {
; #pragma unroll
;                         for (int q = 0; q < 4; ++q) { const float h1 = v[2 * q], h2 = v[2 * q + 1]; v[2 * q] = h1 * cs[q].x - h2 * cs[q].y; v[2 * q + 1] = h2 * cs[q].x + h1 * cs[q].y; }
;                     }
;                     u32x4 w; w.x = pk2(v[0] * sc, v[1] * sc); w.y = pk2(v[2] * sc, v[3] * sc); w.z = pk2(v[4] * sc, v[5] * sc); w.w = pk2(v[6] * sc, v[7] * sc);
;                     *(u32x4*)(P + (size_t)row * NIN + pn * 256 + bj * 128 + wc * 32 + 8 * fq) = w;
;                 }
.LBB0_156:
	s_or_b64 exec, exec, s[28:29]
	v_mov_b32_e32 v168, v60
	v_mov_b32_e32 v169, v61
	v_mov_b32_e32 v170, v62
	v_mov_b32_e32 v171, v63
	v_mov_b32_e32 v172, v56
	v_mov_b32_e32 v173, v57
	v_mov_b32_e32 v174, v58
	v_mov_b32_e32 v175, v59
	s_and_saveexec_b64 s[28:29], s[0:1]
	s_cbranch_execz .LBB0_158
	s_waitcnt vmcnt(2)
	v_pk_mul_f32 v[182:183], v[60:61], v[132:133] op_sel:[1,1] op_sel_hi:[0,1]
	v_pk_fma_f32 v[168:169], v[60:61], v[132:133], v[182:183] op_sel_hi:[1,0,1]
	v_pk_mul_f32 v[150:151], v[60:61], v[132:133]
	v_mov_b32_e32 v168, v135
	v_pk_mul_f32 v[172:173], v[62:63], v[168:169] op_sel:[1,0] op_sel_hi:[0,0]
	v_mov_b32_e32 v168, v129
	v_pk_mul_f32 v[174:175], v[56:57], v[168:169] op_sel:[1,0] op_sel_hi:[0,0]
	v_mul_f32_e32 v168, v59, v131
	v_pk_fma_f32 v[170:171], v[62:63], v[134:135], v[172:173] op_sel_hi:[1,0,1] neg_lo:[0,0,1] neg_hi:[0,0,1]
	v_pk_fma_f32 v[184:185], v[62:63], v[134:135], v[172:173] op_sel_hi:[1,0,1]
	v_pk_fma_f32 v[172:173], v[56:57], v[128:129], v[174:175] op_sel_hi:[1,0,1] neg_lo:[0,0,1] neg_hi:[0,0,1]
	v_pk_fma_f32 v[186:187], v[56:57], v[128:129], v[174:175] op_sel_hi:[1,0,1]
	v_pk_fma_f32 v[174:175], v[58:59], v[130:131], v[168:169] op_sel_hi:[1,1,0] neg_lo:[0,0,1] neg_hi:[0,0,1]
	v_mul_f32_e32 v168, v58, v131
	v_pk_fma_f32 v[188:189], v[58:59], v[130:131], v[168:169] op_sel:[1,0,0] op_sel_hi:[0,1,0]
	v_sub_f32_e32 v168, v150, v182
	v_mov_b32_e32 v171, v185
	v_mov_b32_e32 v173, v187
	v_mov_b32_e32 v175, v188
.LBB0_158:
	s_or_b64 exec, exec, s[28:29]
	v_pk_mul_f32 v[150:151], v[164:165], v[168:169]
	v_readlane_b32 s76, v253, 6
	v_cvt_pk_bf16_f32 v182, v150, v151
	v_pk_mul_f32 v[150:151], v[164:165], v[170:171]
	v_readlane_b32 s77, v253, 7
	v_cvt_pk_bf16_f32 v183, v150, v151
	v_pk_mul_f32 v[150:151], v[164:165], v[172:173]
	v_mov_b32_e32 v170, v52
	v_cvt_pk_bf16_f32 v184, v150, v151
	v_pk_mul_f32 v[150:151], v[164:165], v[174:175]
	v_mov_b32_e32 v171, v53
	v_cvt_pk_bf16_f32 v185, v150, v151
	v_mov_b64_e32 v[150:151], s[74:75]
	v_mad_i64_i32 v[150:151], s[28:29], v176, s72, v[150:151]
	v_lshl_add_u64 v[150:151], s[26:27], 1, v[150:151]
	v_lshl_add_u64 v[150:151], v[150:151], 0, s[76:77]
	v_lshl_add_u64 v[168:169], v[150:151], 0, v[146:147]
	v_mov_b32_e32 v172, v54
	v_mov_b32_e32 v173, v55
	v_mov_b32_e32 v174, v48
	v_mov_b32_e32 v175, v49
	v_mov_b32_e32 v176, v50
	v_mov_b32_e32 v177, v51
	v_readlane_b32 s78, v253, 8
	v_readlane_b32 s79, v253, 9
	v_readlane_b32 s80, v253, 10
	v_readlane_b32 s81, v253, 11
	v_readlane_b32 s82, v253, 12
	v_readlane_b32 s83, v253, 13
	v_readlane_b32 s84, v253, 14
	v_readlane_b32 s85, v253, 15
	v_readlane_b32 s86, v253, 16
	v_readlane_b32 s87, v253, 17
	v_readlane_b32 s88, v253, 18
	v_readlane_b32 s89, v253, 19
	v_readlane_b32 s90, v253, 20
	v_readlane_b32 s91, v253, 21
	global_store_dwordx4 v[168:169], v[182:185], off
	s_and_saveexec_b64 s[28:29], s[0:1]
	s_cbranch_execz .LBB0_160
	s_waitcnt vmcnt(1)
	v_pk_mul_f32 v[182:183], v[52:53], v[132:133] op_sel:[1,1] op_sel_hi:[0,1]
	v_pk_fma_f32 v[170:171], v[52:53], v[132:133], v[182:183] op_sel_hi:[1,0,1]
	v_pk_mul_f32 v[150:151], v[52:53], v[132:133]
	v_mov_b32_e32 v170, v135
	v_pk_mul_f32 v[174:175], v[54:55], v[170:171] op_sel:[1,0] op_sel_hi:[0,0]
	v_mov_b32_e32 v170, v129
	v_pk_mul_f32 v[176:177], v[48:49], v[170:171] op_sel:[1,0] op_sel_hi:[0,0]
	v_mul_f32_e32 v170, v51, v131
	v_pk_fma_f32 v[172:173], v[54:55], v[134:135], v[174:175] op_sel_hi:[1,0,1] neg_lo:[0,0,1] neg_hi:[0,0,1]
	v_pk_fma_f32 v[184:185], v[54:55], v[134:135], v[174:175] op_sel_hi:[1,0,1]
	v_pk_fma_f32 v[174:175], v[48:49], v[128:129], v[176:177] op_sel_hi:[1,0,1] neg_lo:[0,0,1] neg_hi:[0,0,1]
	v_pk_fma_f32 v[186:187], v[48:49], v[128:129], v[176:177] op_sel_hi:[1,0,1]
	v_pk_fma_f32 v[176:177], v[50:51], v[130:131], v[170:171] op_sel_hi:[1,1,0] neg_lo:[0,0,1] neg_hi:[0,0,1]
	v_mul_f32_e32 v170, v50, v131
	v_pk_fma_f32 v[188:189], v[50:51], v[130:131], v[170:171] op_sel:[1,0,0] op_sel_hi:[0,1,0]
	v_sub_f32_e32 v170, v150, v182
	v_mov_b32_e32 v173, v185
	v_mov_b32_e32 v175, v187
	v_mov_b32_e32 v177, v188
.LBB0_160:
	s_or_b64 exec, exec, s[28:29]
	v_pk_mul_f32 v[150:151], v[164:165], v[170:171]
	s_nop 0
	v_cvt_pk_bf16_f32 v170, v150, v151
	v_pk_mul_f32 v[150:151], v[164:165], v[172:173]
	s_nop 0
	v_cvt_pk_bf16_f32 v171, v150, v151
	v_pk_mul_f32 v[150:151], v[164:165], v[174:175]
	s_nop 0
	v_cvt_pk_bf16_f32 v172, v150, v151
	v_pk_mul_f32 v[150:151], v[164:165], v[176:177]
	s_nop 0
	v_cvt_pk_bf16_f32 v173, v150, v151
	global_store_dwordx4 v[168:169], v[170:173], off offset:256
	s_movk_i32 s0, 0x7f70
	v_cmp_gt_i32_e64 s[0:1], s0, v180
	v_add_u32_e32 v176, 0x90, v180
	s_and_b64 s[0:1], s[2:3], s[0:1]
	s_and_saveexec_b64 s[28:29], s[0:1]
	s_cbranch_execz .LBB0_162
	s_waitcnt vmcnt(2)
	v_bfe_u32 v129, v176, 6, 6
	v_and_b32_e32 v128, 0xfdf, v176
	v_cndmask_b32_e64 v129, v155, v129, s[6:7]
	v_lshlrev_b32_e32 v129, 4, v129
	v_lshlrev_b32_e32 v128, 5, v128
	v_cndmask_b32_e32 v128, v128, v129, vcc
	s_and_b64 s[52:53], vcc, exec
	s_cselect_b32 s53, s41, s49
	s_cselect_b32 s52, s40, s48
	v_lshlrev_b32_e32 v128, 3, v128
	v_mov_b32_e32 v129, v147
	v_lshl_add_u64 v[128:129], s[52:53], 0, v[128:129]
	v_mov_b32_e32 v167, v147
	v_lshl_add_u64 v[132:133], v[128:129], 0, v[166:167]
	v_mov_b32_e32 v128, v238
	v_mov_b32_e32 v129, v239
	v_mov_b32_e32 v130, v240
	v_mov_b32_e32 v131, v241
	s_nop 0
	v_mov_b32_e32 v132, v234
	v_mov_b32_e32 v133, v235
	v_mov_b32_e32 v134, v236
	v_mov_b32_e32 v135, v237
; DI unsigned pk2(float lo, float hi) { f32x2 v = {lo, hi}; bf16x2_t b = __builtin_convertvector(v, bf16x2_t); return __builtin_bit_cast(unsigned, b); }
;     DI void operator()(const pg8::f32x4 (&acc)[2][2][4][2], const pg8::Unit& u, int wr, int wc, int fr, int fq) const {
;     ...
;                 const int row = row0 + ai * 128 + m * 16;
;                 f32x2 cs[4];
;                 bool rot = false;
;                 if ((att || ret) && row < M_LAT) {
;                     rot = true;
;                     const int s = row & 4095;
;                     const f32x2* tp;
;                     if (att) { const int pos = (wc & 1) ? (s & 63) : (s >> 6); tp = tatt + pos * 16 + 4 * fq; }
;                     else { tp = tret + (size_t)s * 32 + 16 * (wc & 1) + 4 * fq; }
;                     const f32x4 t0 = *(const f32x4*)tp, t1 = *(const f32x4*)(tp + 2);
;                     cs[0] = (f32x2){t0.x, t0.y}; cs[1] = (f32x2){t0.z, t0.w}; cs[2] = (f32x2){t1.x, t1.y}; cs[3] = (f32x2){t1.z, t1.w};
;                 }
; #pragma unroll
;                 for (int bj = 0; bj < 2; ++bj) {
;                     float v[8];
; #pragma unroll
;                     for (int n = 0; n < 2; ++n)
; #pragma unroll
;                         for (int j = 0; j < 4; ++j) v[n * 4 + j] = acc[ai][bj][m][n][j];
;                     if (rot) {
; #pragma unroll
;                         for (int q = 0; q < 4; ++q) { const float h1 = v[2 * q], h2 = v[2 * q + 1]; v[2 * q] = h1 * cs[q].x - h2 * cs[q].y; v[2 * q + 1] = h2 * cs[q].x + h1 * cs[q].y; }
;                     }
;                     u32x4 w; w.x = pk2(v[0] * sc, v[1] * sc); w.y = pk2(v[2] * sc, v[3] * sc); w.z = pk2(v[4] * sc, v[5] * sc); w.w = pk2(v[6] * sc, v[7] * sc);
;                     *(u32x4*)(P + (size_t)row * NIN + pn * 256 + bj * 128 + wc * 32 + 8 * fq) = w;
;                 }
.LBB0_162:
	s_or_b64 exec, exec, s[28:29]
	v_mov_b32_e32 v168, v44
	v_mov_b32_e32 v169, v45
	v_mov_b32_e32 v170, v46
	v_mov_b32_e32 v171, v47
	v_mov_b32_e32 v172, v40
	v_mov_b32_e32 v173, v41
	v_mov_b32_e32 v174, v42
	v_mov_b32_e32 v175, v43
	s_and_saveexec_b64 s[28:29], s[0:1]
	s_cbranch_execz .LBB0_164
	s_waitcnt vmcnt(2)
	v_pk_mul_f32 v[182:183], v[44:45], v[132:133] op_sel:[1,1] op_sel_hi:[0,1]
	v_pk_fma_f32 v[168:169], v[44:45], v[132:133], v[182:183] op_sel_hi:[1,0,1]
	v_pk_mul_f32 v[150:151], v[44:45], v[132:133]
	v_mov_b32_e32 v168, v135
	v_pk_mul_f32 v[172:173], v[46:47], v[168:169] op_sel:[1,0] op_sel_hi:[0,0]
	v_mov_b32_e32 v168, v129
	v_pk_mul_f32 v[174:175], v[40:41], v[168:169] op_sel:[1,0] op_sel_hi:[0,0]
	v_mul_f32_e32 v168, v43, v131
	v_pk_fma_f32 v[170:171], v[46:47], v[134:135], v[172:173] op_sel_hi:[1,0,1] neg_lo:[0,0,1] neg_hi:[0,0,1]
	v_pk_fma_f32 v[184:185], v[46:47], v[134:135], v[172:173] op_sel_hi:[1,0,1]
	v_pk_fma_f32 v[172:173], v[40:41], v[128:129], v[174:175] op_sel_hi:[1,0,1] neg_lo:[0,0,1] neg_hi:[0,0,1]
	v_pk_fma_f32 v[186:187], v[40:41], v[128:129], v[174:175] op_sel_hi:[1,0,1]
	v_pk_fma_f32 v[174:175], v[42:43], v[130:131], v[168:169] op_sel_hi:[1,1,0] neg_lo:[0,0,1] neg_hi:[0,0,1]
	v_mul_f32_e32 v168, v42, v131
	v_pk_fma_f32 v[188:189], v[42:43], v[130:131], v[168:169] op_sel:[1,0,0] op_sel_hi:[0,1,0]
	v_sub_f32_e32 v168, v150, v182
	v_mov_b32_e32 v171, v185
	v_mov_b32_e32 v173, v187
	v_mov_b32_e32 v175, v188
.LBB0_164:
	s_or_b64 exec, exec, s[28:29]
	v_pk_mul_f32 v[150:151], v[164:165], v[168:169]
	v_readlane_b32 s76, v253, 6
	v_cvt_pk_bf16_f32 v182, v150, v151
	v_pk_mul_f32 v[150:151], v[164:165], v[170:171]
	v_readlane_b32 s77, v253, 7
	v_cvt_pk_bf16_f32 v183, v150, v151
	v_pk_mul_f32 v[150:151], v[164:165], v[172:173]
	v_mov_b32_e32 v170, v36
	v_cvt_pk_bf16_f32 v184, v150, v151
	v_pk_mul_f32 v[150:151], v[164:165], v[174:175]
	v_mov_b32_e32 v171, v37
	v_cvt_pk_bf16_f32 v185, v150, v151
	v_mov_b64_e32 v[150:151], s[74:75]
	v_mad_i64_i32 v[150:151], s[28:29], v176, s72, v[150:151]
	v_lshl_add_u64 v[150:151], s[26:27], 1, v[150:151]
	v_lshl_add_u64 v[150:151], v[150:151], 0, s[76:77]
	v_lshl_add_u64 v[168:169], v[150:151], 0, v[146:147]
	v_mov_b32_e32 v172, v38
	v_mov_b32_e32 v173, v39
	v_mov_b32_e32 v174, v32
	v_mov_b32_e32 v175, v33
	v_mov_b32_e32 v176, v34
	v_mov_b32_e32 v177, v35
	v_readlane_b32 s78, v253, 8
	v_readlane_b32 s79, v253, 9
	v_readlane_b32 s80, v253, 10
	v_readlane_b32 s81, v253, 11
	v_readlane_b32 s82, v253, 12
	v_readlane_b32 s83, v253, 13
	v_readlane_b32 s84, v253, 14
	v_readlane_b32 s85, v253, 15
	v_readlane_b32 s86, v253, 16
	v_readlane_b32 s87, v253, 17
	v_readlane_b32 s88, v253, 18
	v_readlane_b32 s89, v253, 19
	v_readlane_b32 s90, v253, 20
	v_readlane_b32 s91, v253, 21
	global_store_dwordx4 v[168:169], v[182:185], off
	s_and_saveexec_b64 s[28:29], s[0:1]
	s_cbranch_execz .LBB0_166
	s_waitcnt vmcnt(1)
	v_pk_mul_f32 v[182:183], v[36:37], v[132:133] op_sel:[1,1] op_sel_hi:[0,1]
	v_pk_fma_f32 v[170:171], v[36:37], v[132:133], v[182:183] op_sel_hi:[1,0,1]
	v_pk_mul_f32 v[150:151], v[36:37], v[132:133]
	v_mov_b32_e32 v170, v135
	v_pk_mul_f32 v[174:175], v[38:39], v[170:171] op_sel:[1,0] op_sel_hi:[0,0]
	v_mov_b32_e32 v170, v129
	v_pk_mul_f32 v[176:177], v[32:33], v[170:171] op_sel:[1,0] op_sel_hi:[0,0]
	v_mul_f32_e32 v170, v35, v131
	v_pk_fma_f32 v[172:173], v[38:39], v[134:135], v[174:175] op_sel_hi:[1,0,1] neg_lo:[0,0,1] neg_hi:[0,0,1]
	v_pk_fma_f32 v[184:185], v[38:39], v[134:135], v[174:175] op_sel_hi:[1,0,1]
	v_pk_fma_f32 v[174:175], v[32:33], v[128:129], v[176:177] op_sel_hi:[1,0,1] neg_lo:[0,0,1] neg_hi:[0,0,1]
	v_pk_fma_f32 v[186:187], v[32:33], v[128:129], v[176:177] op_sel_hi:[1,0,1]
	v_pk_fma_f32 v[176:177], v[34:35], v[130:131], v[170:171] op_sel_hi:[1,1,0] neg_lo:[0,0,1] neg_hi:[0,0,1]
	v_mul_f32_e32 v170, v34, v131
	v_pk_fma_f32 v[188:189], v[34:35], v[130:131], v[170:171] op_sel:[1,0,0] op_sel_hi:[0,1,0]
	v_sub_f32_e32 v170, v150, v182
	v_mov_b32_e32 v173, v185
	v_mov_b32_e32 v175, v187
	v_mov_b32_e32 v177, v188
.LBB0_166:
	s_or_b64 exec, exec, s[28:29]
	v_pk_mul_f32 v[150:151], v[164:165], v[170:171]
	s_nop 0
	v_cvt_pk_bf16_f32 v170, v150, v151
	v_pk_mul_f32 v[150:151], v[164:165], v[172:173]
	s_nop 0
	v_cvt_pk_bf16_f32 v171, v150, v151
	v_pk_mul_f32 v[150:151], v[164:165], v[174:175]
	s_nop 0
	v_cvt_pk_bf16_f32 v172, v150, v151
	v_pk_mul_f32 v[150:151], v[164:165], v[176:177]
	s_nop 0
	v_cvt_pk_bf16_f32 v173, v150, v151
	global_store_dwordx4 v[168:169], v[170:173], off offset:256
	s_movk_i32 s0, 0x7f60
	v_cmp_gt_i32_e64 s[0:1], s0, v180
	v_add_u32_e32 v176, 0xa0, v180
	s_and_b64 s[0:1], s[2:3], s[0:1]
	s_and_saveexec_b64 s[28:29], s[0:1]
	s_cbranch_execz .LBB0_168
	s_waitcnt vmcnt(2)
	v_bfe_u32 v129, v176, 6, 6
	v_and_b32_e32 v128, 0xfef, v176
	v_cndmask_b32_e64 v129, v157, v129, s[6:7]
	v_lshlrev_b32_e32 v129, 4, v129
	v_lshlrev_b32_e32 v128, 5, v128
	v_cndmask_b32_e32 v128, v128, v129, vcc
	s_and_b64 s[52:53], vcc, exec
	s_cselect_b32 s53, s41, s49
	s_cselect_b32 s52, s40, s48
	v_lshlrev_b32_e32 v128, 3, v128
	v_mov_b32_e32 v129, v147
	v_lshl_add_u64 v[128:129], s[52:53], 0, v[128:129]
	v_mov_b32_e32 v167, v147
	v_lshl_add_u64 v[132:133], v[128:129], 0, v[166:167]
	v_mov_b32_e32 v128, v246
	v_mov_b32_e32 v129, v247
	v_mov_b32_e32 v130, v248
	v_mov_b32_e32 v131, v249
	s_nop 0
	v_mov_b32_e32 v132, v242
	v_mov_b32_e32 v133, v243
	v_mov_b32_e32 v134, v244
	v_mov_b32_e32 v135, v245
; DI unsigned pk2(float lo, float hi) { f32x2 v = {lo, hi}; bf16x2_t b = __builtin_convertvector(v, bf16x2_t); return __builtin_bit_cast(unsigned, b); }
;     DI void operator()(const pg8::f32x4 (&acc)[2][2][4][2], const pg8::Unit& u, int wr, int wc, int fr, int fq) const {
;     ...
;                 const int row = row0 + ai * 128 + m * 16;
;                 f32x2 cs[4];
;                 bool rot = false;
;                 if ((att || ret) && row < M_LAT) {
;                     rot = true;
;                     const int s = row & 4095;
;                     const f32x2* tp;
;                     if (att) { const int pos = (wc & 1) ? (s & 63) : (s >> 6); tp = tatt + pos * 16 + 4 * fq; }
;                     else { tp = tret + (size_t)s * 32 + 16 * (wc & 1) + 4 * fq; }
;                     const f32x4 t0 = *(const f32x4*)tp, t1 = *(const f32x4*)(tp + 2);
;                     cs[0] = (f32x2){t0.x, t0.y}; cs[1] = (f32x2){t0.z, t0.w}; cs[2] = (f32x2){t1.x, t1.y}; cs[3] = (f32x2){t1.z, t1.w};
;                 }
; #pragma unroll
;                 for (int bj = 0; bj < 2; ++bj) {
;                     float v[8];
; #pragma unroll
;                     for (int n = 0; n < 2; ++n)
; #pragma unroll
;                         for (int j = 0; j < 4; ++j) v[n * 4 + j] = acc[ai][bj][m][n][j];
;                     if (rot) {
; #pragma unroll
;                         for (int q = 0; q < 4; ++q) { const float h1 = v[2 * q], h2 = v[2 * q + 1]; v[2 * q] = h1 * cs[q].x - h2 * cs[q].y; v[2 * q + 1] = h2 * cs[q].x + h1 * cs[q].y; }
;                     }
;                     u32x4 w; w.x = pk2(v[0] * sc, v[1] * sc); w.y = pk2(v[2] * sc, v[3] * sc); w.z = pk2(v[4] * sc, v[5] * sc); w.w = pk2(v[6] * sc, v[7] * sc);
;                     *(u32x4*)(P + (size_t)row * NIN + pn * 256 + bj * 128 + wc * 32 + 8 * fq) = w;
;                 }
.LBB0_168:
	s_or_b64 exec, exec, s[28:29]
	v_mov_b32_e32 v168, v28
	v_mov_b32_e32 v169, v29
	v_mov_b32_e32 v170, v30
	v_mov_b32_e32 v171, v31
	v_mov_b32_e32 v172, v24
	v_mov_b32_e32 v173, v25
	v_mov_b32_e32 v174, v26
	v_mov_b32_e32 v175, v27
	s_and_saveexec_b64 s[28:29], s[0:1]
	s_cbranch_execz .LBB0_170
	s_waitcnt vmcnt(2)
	v_pk_mul_f32 v[182:183], v[28:29], v[132:133] op_sel:[1,1] op_sel_hi:[0,1]
	v_pk_fma_f32 v[168:169], v[28:29], v[132:133], v[182:183] op_sel_hi:[1,0,1]
	v_pk_mul_f32 v[150:151], v[28:29], v[132:133]
	v_mov_b32_e32 v168, v135
	v_pk_mul_f32 v[172:173], v[30:31], v[168:169] op_sel:[1,0] op_sel_hi:[0,0]
	v_mov_b32_e32 v168, v129
	v_pk_mul_f32 v[174:175], v[24:25], v[168:169] op_sel:[1,0] op_sel_hi:[0,0]
	v_mul_f32_e32 v168, v27, v131
	v_pk_fma_f32 v[170:171], v[30:31], v[134:135], v[172:173] op_sel_hi:[1,0,1] neg_lo:[0,0,1] neg_hi:[0,0,1]
	v_pk_fma_f32 v[184:185], v[30:31], v[134:135], v[172:173] op_sel_hi:[1,0,1]
	v_pk_fma_f32 v[172:173], v[24:25], v[128:129], v[174:175] op_sel_hi:[1,0,1] neg_lo:[0,0,1] neg_hi:[0,0,1]
	v_pk_fma_f32 v[186:187], v[24:25], v[128:129], v[174:175] op_sel_hi:[1,0,1]
	v_pk_fma_f32 v[174:175], v[26:27], v[130:131], v[168:169] op_sel_hi:[1,1,0] neg_lo:[0,0,1] neg_hi:[0,0,1]
	v_mul_f32_e32 v168, v26, v131
	v_pk_fma_f32 v[188:189], v[26:27], v[130:131], v[168:169] op_sel:[1,0,0] op_sel_hi:[0,1,0]
	v_sub_f32_e32 v168, v150, v182
	v_mov_b32_e32 v171, v185
	v_mov_b32_e32 v173, v187
	v_mov_b32_e32 v175, v188
.LBB0_170:
	s_or_b64 exec, exec, s[28:29]
	v_pk_mul_f32 v[150:151], v[164:165], v[168:169]
	v_readlane_b32 s76, v253, 6
	v_cvt_pk_bf16_f32 v182, v150, v151
	v_pk_mul_f32 v[150:151], v[164:165], v[170:171]
	v_readlane_b32 s77, v253, 7
	v_cvt_pk_bf16_f32 v183, v150, v151
	v_pk_mul_f32 v[150:151], v[164:165], v[172:173]
	v_mov_b32_e32 v170, v20
	v_cvt_pk_bf16_f32 v184, v150, v151
	v_pk_mul_f32 v[150:151], v[164:165], v[174:175]
	v_mov_b32_e32 v171, v21
	v_cvt_pk_bf16_f32 v185, v150, v151
	v_mov_b64_e32 v[150:151], s[74:75]
	v_mad_i64_i32 v[150:151], s[28:29], v176, s72, v[150:151]
	v_lshl_add_u64 v[150:151], s[26:27], 1, v[150:151]
	v_lshl_add_u64 v[150:151], v[150:151], 0, s[76:77]
	v_lshl_add_u64 v[168:169], v[150:151], 0, v[146:147]
	v_mov_b32_e32 v172, v22
	v_mov_b32_e32 v173, v23
	v_mov_b32_e32 v174, v16
	v_mov_b32_e32 v175, v17
	v_mov_b32_e32 v176, v18
	v_mov_b32_e32 v177, v19
	v_readlane_b32 s78, v253, 8
	v_readlane_b32 s79, v253, 9
	v_readlane_b32 s80, v253, 10
	v_readlane_b32 s81, v253, 11
	v_readlane_b32 s82, v253, 12
	v_readlane_b32 s83, v253, 13
	v_readlane_b32 s84, v253, 14
	v_readlane_b32 s85, v253, 15
	v_readlane_b32 s86, v253, 16
	v_readlane_b32 s87, v253, 17
	v_readlane_b32 s88, v253, 18
	v_readlane_b32 s89, v253, 19
	v_readlane_b32 s90, v253, 20
	v_readlane_b32 s91, v253, 21
	global_store_dwordx4 v[168:169], v[182:185], off
	s_and_saveexec_b64 s[28:29], s[0:1]
	s_cbranch_execz .LBB0_172
	s_waitcnt vmcnt(1)
	v_pk_mul_f32 v[182:183], v[20:21], v[132:133] op_sel:[1,1] op_sel_hi:[0,1]
	v_pk_fma_f32 v[170:171], v[20:21], v[132:133], v[182:183] op_sel_hi:[1,0,1]
	v_pk_mul_f32 v[150:151], v[20:21], v[132:133]
	v_mov_b32_e32 v170, v135
	v_pk_mul_f32 v[174:175], v[22:23], v[170:171] op_sel:[1,0] op_sel_hi:[0,0]
	v_mov_b32_e32 v170, v129
	v_pk_mul_f32 v[176:177], v[16:17], v[170:171] op_sel:[1,0] op_sel_hi:[0,0]
	v_mul_f32_e32 v170, v19, v131
	v_pk_fma_f32 v[172:173], v[22:23], v[134:135], v[174:175] op_sel_hi:[1,0,1] neg_lo:[0,0,1] neg_hi:[0,0,1]
	v_pk_fma_f32 v[184:185], v[22:23], v[134:135], v[174:175] op_sel_hi:[1,0,1]
	v_pk_fma_f32 v[174:175], v[16:17], v[128:129], v[176:177] op_sel_hi:[1,0,1] neg_lo:[0,0,1] neg_hi:[0,0,1]
	v_pk_fma_f32 v[186:187], v[16:17], v[128:129], v[176:177] op_sel_hi:[1,0,1]
	v_pk_fma_f32 v[176:177], v[18:19], v[130:131], v[170:171] op_sel_hi:[1,1,0] neg_lo:[0,0,1] neg_hi:[0,0,1]
	v_mul_f32_e32 v170, v18, v131
	v_pk_fma_f32 v[188:189], v[18:19], v[130:131], v[170:171] op_sel:[1,0,0] op_sel_hi:[0,1,0]
	v_sub_f32_e32 v170, v150, v182
	v_mov_b32_e32 v173, v185
	v_mov_b32_e32 v175, v187
	v_mov_b32_e32 v177, v188
.LBB0_172:
	s_or_b64 exec, exec, s[28:29]
	v_pk_mul_f32 v[150:151], v[164:165], v[170:171]
	s_nop 0
	v_cvt_pk_bf16_f32 v170, v150, v151
	v_pk_mul_f32 v[150:151], v[164:165], v[172:173]
	s_nop 0
	v_cvt_pk_bf16_f32 v171, v150, v151
	v_pk_mul_f32 v[150:151], v[164:165], v[174:175]
	s_nop 0
	v_cvt_pk_bf16_f32 v172, v150, v151
	v_pk_mul_f32 v[150:151], v[164:165], v[176:177]
	s_nop 0
	v_cvt_pk_bf16_f32 v173, v150, v151
	global_store_dwordx4 v[168:169], v[170:173], off offset:256
	s_movk_i32 s0, 0x7f50
	v_cmp_gt_i32_e64 s[0:1], s0, v180
	v_add_u32_e32 v174, 0xb0, v180
	s_and_b64 s[0:1], s[2:3], s[0:1]
	s_and_saveexec_b64 s[2:3], s[0:1]
	s_cbranch_execz .LBB0_174
	s_waitcnt vmcnt(2)
	v_bfe_u32 v129, v174, 6, 6
	v_and_b32_e32 v128, 0xfff, v174
	v_cndmask_b32_e64 v129, v159, v129, s[6:7]
	v_lshlrev_b32_e32 v129, 4, v129
	v_lshlrev_b32_e32 v128, 5, v128
	v_cndmask_b32_e32 v128, v128, v129, vcc
	s_and_b64 s[28:29], vcc, exec
	s_cselect_b32 s29, s41, s49
	s_cselect_b32 s28, s40, s48
	v_lshlrev_b32_e32 v128, 3, v128
	v_mov_b32_e32 v129, v147
	v_lshl_add_u64 v[128:129], s[28:29], 0, v[128:129]
	v_mov_b32_e32 v167, v147
	v_lshl_add_u64 v[132:133], v[128:129], 0, v[166:167]
	global_load_dwordx4 v[128:131], v[132:133], off offset:16
	s_nop 0
	global_load_dwordx4 v[132:135], v[132:133], off

; DI unsigned pk2(float lo, float hi) { f32x2 v = {lo, hi}; bf16x2_t b = __builtin_convertvector(v, bf16x2_t); return __builtin_bit_cast(unsigned, b); }
;     DI void operator()(const pg8::f32x4 (&acc)[2][2][4][2], const pg8::Unit& u, int wr, int wc, int fr, int fq) const {
;     ...
; #pragma unroll
;                 for (int bj = 0; bj < 2; ++bj) {
;                     float v[8];
; #pragma unroll
;                     for (int n = 0; n < 2; ++n)
; #pragma unroll
;                         for (int j = 0; j < 4; ++j) v[n * 4 + j] = acc[ai][bj][m][n][j];
;                     if (rot) {
; #pragma unroll
;                         for (int q = 0; q < 4; ++q) { const float h1 = v[2 * q], h2 = v[2 * q + 1]; v[2 * q] = h1 * cs[q].x - h2 * cs[q].y; v[2 * q + 1] = h2 * cs[q].x + h1 * cs[q].y; }
;                     }
;                     u32x4 w; w.x = pk2(v[0] * sc, v[1] * sc); w.y = pk2(v[2] * sc, v[3] * sc); w.z = pk2(v[4] * sc, v[5] * sc); w.w = pk2(v[6] * sc, v[7] * sc);
;                     *(u32x4*)(P + (size_t)row * NIN + pn * 256 + bj * 128 + wc * 32 + 8 * fq) = w;
;                 }
.LBB0_176:
	s_or_b64 exec, exec, s[2:3]
	v_pk_mul_f32 v[150:151], v[164:165], v[166:167]
	v_readlane_b32 s76, v253, 6
	v_cvt_pk_bf16_f32 v182, v150, v151
	v_pk_mul_f32 v[150:151], v[164:165], v[168:169]
	v_readlane_b32 s77, v253, 7
	v_cvt_pk_bf16_f32 v183, v150, v151
	v_pk_mul_f32 v[150:151], v[164:165], v[170:171]
	v_mov_b32_e32 v168, v4
	v_cvt_pk_bf16_f32 v184, v150, v151
	v_pk_mul_f32 v[150:151], v[164:165], v[172:173]
	v_mov_b32_e32 v169, v5
	v_cvt_pk_bf16_f32 v185, v150, v151
	v_mov_b64_e32 v[150:151], s[74:75]
	v_mad_i64_i32 v[150:151], s[2:3], v174, s72, v[150:151]
	v_lshl_add_u64 v[150:151], s[26:27], 1, v[150:151]
	v_lshl_add_u64 v[150:151], v[150:151], 0, s[76:77]
	v_lshl_add_u64 v[166:167], v[150:151], 0, v[146:147]
	v_mov_b32_e32 v170, v6
	v_mov_b32_e32 v171, v7
	v_mov_b32_e32 v172, v0
	v_mov_b32_e32 v173, v1
	v_mov_b32_e32 v174, v2
	v_mov_b32_e32 v175, v3
	v_readlane_b32 s78, v253, 8
	v_readlane_b32 s79, v253, 9
	v_readlane_b32 s80, v253, 10
	v_readlane_b32 s81, v253, 11
	v_readlane_b32 s82, v253, 12
	v_readlane_b32 s83, v253, 13
	v_readlane_b32 s84, v253, 14
	v_readlane_b32 s85, v253, 15
	v_readlane_b32 s86, v253, 16
	v_readlane_b32 s87, v253, 17
	v_readlane_b32 s88, v253, 18
	v_readlane_b32 s89, v253, 19
	v_readlane_b32 s90, v253, 20
	v_readlane_b32 s91, v253, 21
	global_store_dwordx4 v[166:167], v[182:185], off
	s_and_saveexec_b64 s[2:3], s[0:1]
	s_cbranch_execz .LBB0_178
	s_waitcnt vmcnt(1)
	v_pk_mul_f32 v[176:177], v[4:5], v[132:133] op_sel:[1,1] op_sel_hi:[0,1]
	v_pk_mul_f32 v[150:151], v[4:5], v[132:133]
	v_pk_fma_f32 v[168:169], v[4:5], v[132:133], v[176:177] op_sel_hi:[1,0,1]
	v_mov_b32_e32 v132, v135
	v_pk_mul_f32 v[132:133], v[6:7], v[132:133] op_sel:[1,0] op_sel_hi:[0,0]
	v_pk_fma_f32 v[170:171], v[6:7], v[134:135], v[132:133] op_sel_hi:[1,0,1] neg_lo:[0,0,1] neg_hi:[0,0,1]
	v_pk_fma_f32 v[132:133], v[6:7], v[134:135], v[132:133] op_sel_hi:[1,0,1]
	v_sub_f32_e32 v168, v150, v176
	v_mov_b32_e32 v132, v129
	v_pk_mul_f32 v[134:135], v[0:1], v[132:133] op_sel:[1,0] op_sel_hi:[0,0]
	v_pk_fma_f32 v[172:173], v[0:1], v[128:129], v[134:135] op_sel_hi:[1,0,1] neg_lo:[0,0,1] neg_hi:[0,0,1]
	v_pk_fma_f32 v[128:129], v[0:1], v[128:129], v[134:135] op_sel_hi:[1,0,1]
	v_mov_b32_e32 v171, v133
	v_mul_f32_e32 v128, v3, v131
	v_pk_fma_f32 v[174:175], v[2:3], v[130:131], v[128:129] op_sel_hi:[1,1,0] neg_lo:[0,0,1] neg_hi:[0,0,1]
	v_mul_f32_e32 v128, v2, v131
	v_pk_fma_f32 v[130:131], v[2:3], v[130:131], v[128:129] op_sel:[1,0,0] op_sel_hi:[0,1,0]
	v_mov_b32_e32 v173, v129
	v_mov_b32_e32 v175, v130
